# diff-attention tile loop: two barriers per tile, wave halves staggered by one barrier, 4-stage K/V ring with prefetch distance 2
# speedup vs baseline: 1.0047x; 1.0047x over previous
; #define LAS __attribute__((address_space(3)))
; #define ATT_GLOAD(kt) do { _Pragma("unroll") for (int i = 0; i < NCH; ++i) { const size_t go = goff + (size_t)((kt) * 64 + i * (512 / CPR)) * kvpitch; \
;         kreg[i] = *(const u32x4*)(Kp + go); vreg[i] = *(const u32x4*)(Vp + go); } } while (0)
; template <bool DIFF> ...
;     ...
;     if (DIFF) { const bf16_t* qrow = Qp + (size_t)(qr + l32) * qpitch + c * 64 + hi * 8;
; #pragma unroll
;       for (int ks = 0; ks < (DIFF ? NKS : 1); ++ks) qf[ks] = *(const bf16x8*)(qrow + ks * 16); }
;     f32x16 o[4];
; #pragma unroll
;     for (int i = 0; i < 4; ++i)
; #pragma unroll
;         for (int r = 0; r < 16; ++r) o[i][r] = 0.f;
;     float m_run = -INFINITY, l_run = 0.f;
;     u32x4 kreg[NCH], vreg[NCH];
;     const int srow = tid / CPR, sch = tid % CPR;
;     const size_t goff = (size_t)srow * kvpitch + sch * 8;
;     const int loffk = srow * KSTR + sch * 16, loffv = KBY + srow * VSTR + sch * 16;
;     ...
;     constexpr int DSTG = 32768;
;     const int dch = (lane & 15) ^ ((((lane >> 4) & 3) << 2) | (wid & 3));
;     ...
;     __syncthreads();
;     if (DIFF) { ATT_DMA(nkt - 1, 0); }
;     else { ATT_GLOAD(0);
; #pragma unroll
;         for (int i = 0; i < 8; ++i) { const int id = tid + 512 * i, row = id >> 5, ch = id & 31;
;             *(LAS u32x4*)(lds + QOFF + row * QSTR + ch * 16) = *(const u32x4*)(Qp + (size_t)row * qpitch + ch * 8); }
;     }
;     const int wrow = qpos0 + qr;
;     f32x16 biasv;
;     { const float beta = DIFF ? sl2 / sc2 : 0.f;
; #pragma unroll
;       for (int r = 0; r < 16; ++r) biasv[r] = beta * (float)((r >> 2) * 8 + (r & 3) + hi * 4 - l32); }
.LBB0_111:
	s_xor_b64 s[30:31], s[0:1], -1
	s_and_b64 s[0:1], s[0:1], exec
	s_cselect_b32 s0, s45, s5
	s_lshl_b32 s25, s0, 7
	s_mul_i32 s0, s0, 0xb0000
	v_mov_b32_e32 v18, v187
	s_add_u32 s0, s16, s0
	s_addc_u32 s1, s17, 0
	v_readfirstlane_b32 s26, v18
	s_ashr_i32 s14, s26, 6
	s_and_b32 s65, s14, 3
	s_lshl_b32 s22, s65, 5
	v_and_b32_e32 v19, 31, v18
	v_or_b32_e32 v183, s22, v19
	v_mov_b64_e32 v[2:3], s[0:1]
	s_movk_i32 s2, 0x1600
	s_ashr_i32 s64, s26, 8
	v_mad_u64_u32 v[2:3], s[0:1], v183, s2, v[2:3]
	s_lshl_b32 s0, s64, 6
	v_bfe_u32 v20, v18, 5, 1
	s_ashr_i32 s1, s0, 31
	v_lshl_add_u64 v[2:3], s[0:1], 1, v[2:3]
	v_lshlrev_b32_e32 v0, 4, v20
	v_lshl_add_u64 v[2:3], v[2:3], 0, v[0:1]
	v_bfe_u32 v21, v18, 4, 2
	global_load_dwordx4 v[114:117], v[2:3], off
	global_load_dwordx4 v[118:121], v[2:3], off offset:32
	global_load_dwordx4 v[122:125], v[2:3], off offset:64
	global_load_dwordx4 v[126:129], v[2:3], off offset:96
	v_and_b32_e32 v0, 15, v18
	v_lshlrev_b32_e32 v2, 2, v21
	s_or_b32 s20, s25, 64
	v_bitop3_b32 v22, v2, v0, s65 bitop3:0x36
	v_or_b32_e32 v6, s20, v21
	s_lshl_b32 s23, s14, 2
	v_lshlrev_b32_e32 v0, 3, v22
	v_add_u32_e32 v2, s23, v6
	s_movk_i32 s3, 0xb00
	v_mad_i64_i32 v[2:3], s[0:1], v2, s3, v[0:1]
	s_lshl_b32 s21, s14, 10
	v_lshl_add_u64 v[2:3], v[2:3], 1, s[16:17]
	s_mov_b64 s[38:39], 0x400
	s_add_i32 s0, s21, 0
	v_lshl_add_u64 v[4:5], v[2:3], 0, s[38:39]
	s_mov_b32 m0, s0
	s_mov_b64 s[36:37], 0x800
	s_barrier
	global_load_lds_dwordx4 v[4:5], off
	v_lshl_add_u64 v[2:3], v[2:3], 0, s[36:37]
	s_add_i32 m0, s0, 0x4000
	s_add_i32 s14, s14, 8
	global_load_lds_dwordx4 v[2:3], off
	v_lshl_add_u32 v2, s14, 2, v6
	v_mad_i64_i32 v[2:3], s[0:1], v2, s3, v[0:1]
	s_lshl_b32 s14, s14, 10
	v_lshl_add_u64 v[2:3], v[2:3], 1, s[16:17]
	s_add_i32 s0, s14, 0
	v_lshl_add_u64 v[4:5], v[2:3], 0, s[38:39]
	s_mov_b32 m0, s0
	v_lshl_add_u64 v[2:3], v[2:3], 0, s[36:37]
	global_load_lds_dwordx4 v[4:5], off
	s_add_i32 m0, s0, 0x4000
	v_lshlrev_b32_e32 v184, 2, v20
	global_load_lds_dwordx4 v[2:3], off
	v_sub_u32_e32 v0, v184, v19
	v_add_u32_e32 v4, 2, v0
	v_add_u32_e32 v5, 3, v0
	v_cvt_f32_i32_e32 v5, v5
	v_cvt_f32_i32_e32 v4, v4
	v_add_u32_e32 v3, 1, v0
	v_add_u32_e32 v6, 8, v0
	v_add_u32_e32 v7, 9, v0
	v_add_u32_e32 v8, 10, v0
	v_add_u32_e32 v9, 11, v0
	v_add_u32_e32 v10, 16, v0
	v_add_u32_e32 v11, 17, v0
	v_add_u32_e32 v12, 18, v0
	v_add_u32_e32 v13, 19, v0
	v_add_u32_e32 v14, 24, v0
	v_add_u32_e32 v15, 25, v0
	v_add_u32_e32 v16, 26, v0
	v_add_u32_e32 v17, 27, v0
	v_cvt_f32_i32_e32 v2, v0
	v_cvt_f32_i32_e32 v3, v3
	v_cvt_f32_i32_e32 v7, v7
	v_cvt_f32_i32_e32 v6, v6
	v_cvt_f32_i32_e32 v9, v9
	v_cvt_f32_i32_e32 v8, v8
	v_cvt_f32_i32_e32 v11, v11
	v_cvt_f32_i32_e32 v10, v10
	v_cvt_f32_i32_e32 v13, v13
	v_cvt_f32_i32_e32 v15, v15
	v_cvt_f32_i32_e32 v17, v17
	v_cvt_f32_i32_e32 v16, v16
	v_cvt_f32_i32_e32 v14, v14
	v_cvt_f32_i32_e32 v12, v12
	v_mov_b32_e32 v163, v162
	v_pk_mul_f32 v[68:69], v[162:163], v[4:5]
	v_bfe_u32 v4, v18, 2, 2
	v_lshlrev_b32_e32 v5, 8, v4
	v_pk_mul_f32 v[80:81], v[162:163], v[16:17]
	v_pk_mul_f32 v[78:79], v[162:163], v[14:15]
	v_pk_mul_f32 v[76:77], v[162:163], v[12:13]
	v_pk_mul_f32 v[74:75], v[162:163], v[10:11]
	v_pk_mul_f32 v[72:73], v[162:163], v[8:9]
	v_pk_mul_f32 v[70:71], v[162:163], v[6:7]
	v_pk_mul_f32 v[66:67], v[164:165], v[2:3]
	v_lshlrev_b32_e32 v3, 2, v18
	v_lshl_or_b32 v163, v20, 10, v5
	v_lshrrev_b32_e32 v5, 3, v18
	s_lshl_b32 s0, s64, 3
	v_and_or_b32 v3, v3, 12, v4
	v_and_b32_e32 v5, 2, v5
	v_bfe_u32 v6, v18, 1, 1
	v_lshlrev_b32_e32 v0, 8, v19
	v_or_b32_e32 v2, s0, v20
	v_bitop3_b32 v7, v5, v20, v6 bitop3:0x36
	v_lshlrev_b32_e32 v199, 6, v4
	v_bitop3_b32 v4, s0, v3, v20 bitop3:0x36
	v_lshlrev_b32_e32 v186, 4, v7
	v_lshlrev_b32_e32 v7, 3, v18
	v_lshl_add_u32 v200, v4, 4, v0
	v_bitop3_b32 v4, v2, v3, 2 bitop3:0x36
	v_and_b32_e32 v197, 8, v7
	v_or_b32_e32 v7, 2, v20
	v_lshl_add_u32 v201, v4, 4, v0
	v_bitop3_b32 v4, v2, v3, 4 bitop3:0x36
	s_add_i32 s23, s23, s25
	v_bitop3_b32 v5, v5, v7, v6 bitop3:0x36
	v_lshl_add_u32 v202, v4, 4, v0
	v_bitop3_b32 v2, v2, v3, 6 bitop3:0x36
	v_or_b32_e32 v4, s23, v21
	v_lshlrev_b32_e32 v198, 4, v5
	v_lshl_add_u32 v203, v2, 4, v0
	v_add_u32_e32 v5, 32, v4
	v_mov_b64_e32 v[2:3], s[18:19]
	v_mad_i64_i32 v[166:167], s[0:1], v5, s2, v[2:3]
	v_mad_i64_i32 v[168:169], s[0:1], v4, s2, v[2:3]
	s_sub_i32 s0, s22, 64
	s_nop 0
	v_or_b32_e32 v2, s0, v19
	v_mov_b32_e32 v50, v1
	v_mov_b32_e32 v51, v1
	v_and_b32_e32 v185, 63, v18
	v_lshlrev_b32_e32 v0, 4, v22
	v_sub_u32_e32 v204, v2, v184
	v_mov_b32_e32 v52, v1
	v_mov_b32_e32 v53, v1
	v_mov_b32_e32 v54, v1
	v_mov_b32_e32 v55, v1
	v_mov_b32_e32 v56, v1
	v_mov_b32_e32 v57, v1
	v_mov_b32_e32 v58, v1
	v_mov_b32_e32 v59, v1
	v_mov_b32_e32 v60, v1
	v_mov_b32_e32 v61, v1
	v_mov_b32_e32 v62, v1
	v_mov_b32_e32 v63, v1
	v_mov_b32_e32 v64, v1
	v_mov_b32_e32 v65, v1
	v_mov_b64_e32 v[34:35], v[50:51]
	v_mov_b64_e32 v[18:19], v[50:51]
	v_mov_b64_e32 v[2:3], v[50:51]
	s_or_b32 s15, s22, s25
	s_mov_b32 s28, 0
	s_sub_i32 s24, 0, s22
	s_mov_b32 s22, 0
	v_xor_b32_e32 v206, 64, v199
	v_xor_b32_e32 v207, 0x80, v199
	v_xor_b32_e32 v208, 0xc0, v199
	v_mov_b32_e32 v209, 0xff800000
	v_mov_b32_e32 v205, 0
	v_mov_b64_e32 v[36:37], v[52:53]
	v_mov_b64_e32 v[38:39], v[54:55]
	v_mov_b64_e32 v[40:41], v[56:57]
	v_mov_b64_e32 v[42:43], v[58:59]
	v_mov_b64_e32 v[44:45], v[60:61]
	v_mov_b64_e32 v[46:47], v[62:63]
	v_mov_b64_e32 v[48:49], v[64:65]
	v_mov_b64_e32 v[20:21], v[52:53]
	v_mov_b64_e32 v[22:23], v[54:55]
	v_mov_b64_e32 v[24:25], v[56:57]
	v_mov_b64_e32 v[26:27], v[58:59]
	v_mov_b64_e32 v[28:29], v[60:61]
	v_mov_b64_e32 v[30:31], v[62:63]
	v_mov_b64_e32 v[32:33], v[64:65]
	v_mov_b64_e32 v[4:5], v[52:53]
	v_mov_b64_e32 v[6:7], v[54:55]
	v_mov_b64_e32 v[8:9], v[56:57]
	v_mov_b64_e32 v[10:11], v[58:59]
	v_mov_b64_e32 v[12:13], v[60:61]
	v_mov_b64_e32 v[14:15], v[62:63]
	v_mov_b64_e32 v[16:17], v[64:65]
	v_lshl_add_u64 v[82:83], v[168:169], 0, v[0:1]
	s_add_i32 s0, s21, 0x8000
	v_lshl_add_u64 v[84:85], v[82:83], 0, s[42:43]
	s_mov_b32 m0, s0
	v_lshl_add_u64 v[82:83], v[82:83], 0, s[6:7]
	global_load_lds_dwordx4 v[84:85], off
	s_add_i32 m0, s0, 0x4000
	s_add_i32 s0, s14, 0x8000
	global_load_lds_dwordx4 v[82:83], off
	v_lshl_add_u64 v[82:83], v[166:167], 0, v[0:1]
	v_lshl_add_u64 v[84:85], v[82:83], 0, s[42:43]
	s_mov_b32 m0, s0
	v_lshl_add_u64 v[82:83], v[82:83], 0, s[6:7]
	global_load_lds_dwordx4 v[84:85], off
	s_add_i32 m0, s0, 0x4000
	s_nop 0
	global_load_lds_dwordx4 v[82:83], off
	v_lshl_add_u64 v[166:167], v[166:167], 0, s[8:9]
	v_lshl_add_u64 v[168:169], v[168:169], 0, s[8:9]
	s_waitcnt vmcnt(4)
	s_cmp_eq_u32 s64, 1
	s_cbranch_scc0 .Latt_pro_a
	s_barrier

; template <bool DIFF> ...
;     ...
;         if (DIFF) asm volatile("s_waitcnt vmcnt(0)" ::: "memory");
;         __syncthreads();
.LBB0_112:
	s_add_i32 s0, s20, s22
	s_cmp_lt_u32 s0, 0x80
	s_cbranch_scc1 .Latt_m0
	s_waitcnt vmcnt(4)
	s_branch .Latt_m1

; __device__ __forceinline__ unsigned cvtpk(float lo, float hi) { f32x2_t v = {lo, hi}; bf16x2_t b = __builtin_convertvector(v, bf16x2_t); return __builtin_bit_cast(unsigned, b); }
; #define ATT_MMAG(F, dvb) do { _Pragma("unroll") for (int j = 0; j < 4; ++j) o[dvb] = __builtin_amdgcn_mfma_f32_32x32x16_bf16(F[j], pb[j >> 1][j & 1], o[dvb], 0, 0, 0); } while (0)
; template <bool DIFF> ...
;     ...
;             const float d0 = c0 - m_run, d1 = c1 - m_run;
;             float rs0 = 0.f, rs1 = 0.f;
; #pragma unroll
;             for (int r = 0; r < 16; ++r) { s0[r] = __builtin_amdgcn_exp2f(__builtin_fmaf(s0[r], sc2, d0)); s1[r] = __builtin_amdgcn_exp2f(__builtin_fmaf(s1[r], sc2, d1)); rs0 += s0[r]; rs1 += s1[r]; }
;             l_run += rs0 + rs1;
;             bf16x8 pb[2][2];
; #pragma unroll
;             for (int g = 0; g < 2; ++g) {
;                 u32x4 w0, w1;
;                 w0.x = cvtpk(s0[8 * g], s0[8 * g + 1]); w0.y = cvtpk(s0[8 * g + 2], s0[8 * g + 3]); w0.z = cvtpk(s0[8 * g + 4], s0[8 * g + 5]); w0.w = cvtpk(s0[8 * g + 6], s0[8 * g + 7]);
;                 w1.x = cvtpk(s1[8 * g], s1[8 * g + 1]); w1.y = cvtpk(s1[8 * g + 2], s1[8 * g + 3]); w1.z = cvtpk(s1[8 * g + 4], s1[8 * g + 5]); w1.w = cvtpk(s1[8 * g + 6], s1[8 * g + 7]);
;                 pb[0][g] = __builtin_bit_cast(bf16x8, w0); pb[1][g] = __builtin_bit_cast(bf16x8, w1);
;             }
;             __builtin_amdgcn_sched_barrier(0);
;             ATT_MMAG(fa, 0); ATT_LOADG(fa, 2); __builtin_amdgcn_sched_barrier(0); ATT_MMAG(fb, 1); ATT_LOADG(fb, 3); __builtin_amdgcn_sched_barrier(0); ATT_MMAG(fa, 2); ATT_MMAG(fb, 3);
.Latt_m1:
	s_barrier
	v_sub_f32_e32 v227, v213, v209
	v_sub_f32_e32 v226, v212, v209
	v_fmamk_f32 v82, v82, 0x3e38aa3b, v227
	v_fmamk_f32 v98, v98, 0x3e38aa3b, v226
	v_exp_f32_e32 v213, v82
	v_fmamk_f32 v82, v99, 0x3e38aa3b, v226
	v_exp_f32_e32 v212, v98
	v_exp_f32_e32 v98, v82
	v_fmamk_f32 v82, v83, 0x3e38aa3b, v227
	v_exp_f32_e32 v99, v82
	v_fmamk_f32 v82, v100, 0x3e38aa3b, v226
	v_exp_f32_e32 v214, v82
	v_fmamk_f32 v82, v84, 0x3e38aa3b, v227
	v_exp_f32_e32 v215, v82
	v_fmamk_f32 v82, v101, 0x3e38aa3b, v226
	v_exp_f32_e32 v84, v82
	v_fmamk_f32 v82, v85, 0x3e38aa3b, v227
	v_exp_f32_e32 v85, v82
	v_fmamk_f32 v82, v102, 0x3e38aa3b, v226
	v_exp_f32_e32 v100, v82
	v_fmamk_f32 v82, v86, 0x3e38aa3b, v227
	v_exp_f32_e32 v101, v82
	v_fmamk_f32 v82, v103, 0x3e38aa3b, v226
	v_exp_f32_e32 v102, v82
	v_fmamk_f32 v82, v87, 0x3e38aa3b, v227
	v_exp_f32_e32 v103, v82
	v_fmamk_f32 v82, v104, 0x3e38aa3b, v226
	v_exp_f32_e32 v216, v82
	v_fmamk_f32 v82, v88, 0x3e38aa3b, v227
	v_exp_f32_e32 v217, v82
	v_fmamk_f32 v82, v105, 0x3e38aa3b, v226
	v_exp_f32_e32 v104, v82
	v_fmamk_f32 v82, v89, 0x3e38aa3b, v227
	v_exp_f32_e32 v105, v82
	v_fmamk_f32 v82, v106, 0x3e38aa3b, v226
	v_exp_f32_e32 v218, v82
	v_fmamk_f32 v82, v90, 0x3e38aa3b, v227
	v_exp_f32_e32 v219, v82
	v_fmamk_f32 v82, v107, 0x3e38aa3b, v226
	v_exp_f32_e32 v106, v82
	v_fmamk_f32 v82, v91, 0x3e38aa3b, v227
	v_exp_f32_e32 v107, v82
	v_fmamk_f32 v82, v108, 0x3e38aa3b, v226
	v_exp_f32_e32 v220, v82
	v_fmamk_f32 v82, v92, 0x3e38aa3b, v227
	v_exp_f32_e32 v221, v82
	v_fmamk_f32 v82, v109, 0x3e38aa3b, v226
	v_exp_f32_e32 v108, v82
	v_fmamk_f32 v82, v93, 0x3e38aa3b, v227
	v_exp_f32_e32 v109, v82
	v_fmamk_f32 v82, v110, 0x3e38aa3b, v226
	v_exp_f32_e32 v222, v82
	v_fmamk_f32 v82, v94, 0x3e38aa3b, v227
	v_exp_f32_e32 v223, v82
	v_fmamk_f32 v82, v111, 0x3e38aa3b, v226
	v_exp_f32_e32 v110, v82
	v_fmamk_f32 v82, v95, 0x3e38aa3b, v227
	v_pk_add_f32 v[88:89], v[212:213], 0 op_sel_hi:[1,0]
	v_exp_f32_e32 v111, v82
	v_fmamk_f32 v82, v112, 0x3e38aa3b, v226
	v_pk_add_f32 v[88:89], v[98:99], v[88:89]
	v_exp_f32_e32 v224, v82
	v_fmamk_f32 v82, v96, 0x3e38aa3b, v227
	v_pk_add_f32 v[88:89], v[214:215], v[88:89]
	v_exp_f32_e32 v225, v82
	v_cvt_pk_bf16_f32 v82, v212, v98
	v_cvt_pk_bf16_f32 v86, v213, v99
	v_pk_add_f32 v[98:99], v[84:85], v[88:89]
	v_fmac_f32_e32 v226, 0x3e38aa3b, v113
	v_pk_add_f32 v[98:99], v[100:101], v[98:99]
	v_fmac_f32_e32 v227, 0x3e38aa3b, v97
	v_pk_add_f32 v[98:99], v[102:103], v[98:99]
	v_exp_f32_e32 v112, v226
	v_pk_add_f32 v[98:99], v[216:217], v[98:99]
	v_exp_f32_e32 v113, v227
	v_pk_add_f32 v[98:99], v[104:105], v[98:99]
	v_cvt_pk_bf16_f32 v83, v214, v84
	v_pk_add_f32 v[98:99], v[218:219], v[98:99]
	v_cvt_pk_bf16_f32 v87, v215, v85
	v_pk_add_f32 v[98:99], v[106:107], v[98:99]
	v_cvt_pk_bf16_f32 v84, v100, v102
	v_pk_add_f32 v[98:99], v[220:221], v[98:99]
	v_cvt_pk_bf16_f32 v85, v216, v104
	v_pk_add_f32 v[98:99], v[108:109], v[98:99]
	v_cvt_pk_bf16_f32 v88, v101, v103
	v_pk_add_f32 v[98:99], v[222:223], v[98:99]
	v_cvt_pk_bf16_f32 v89, v217, v105
	v_pk_add_f32 v[98:99], v[110:111], v[98:99]
	v_cvt_pk_bf16_f32 v90, v218, v106
	v_pk_add_f32 v[98:99], v[224:225], v[98:99]
	v_cvt_pk_bf16_f32 v91, v220, v108
	v_pk_add_f32 v[98:99], v[112:113], v[98:99]
	v_cvt_pk_bf16_f32 v92, v222, v110
	v_cvt_pk_bf16_f32 v93, v224, v112
	v_cvt_pk_bf16_f32 v94, v219, v107
	v_cvt_pk_bf16_f32 v95, v221, v109
	v_cvt_pk_bf16_f32 v96, v223, v111
	v_cvt_pk_bf16_f32 v97, v225, v113
	v_add_f32_e32 v212, v98, v99
	v_mfma_f32_32x32x16_bf16 v[50:65], v[150:153], v[82:85], v[50:65]
	v_add_u32_e32 v110, v210, v207
	v_add_u32_e32 v112, v211, v207
	ds_read_b64_tr_b16 v[98:99], v110 offset:16384
	ds_read_b64_tr_b16 v[100:101], v112 offset:18432
	ds_read_b64_tr_b16 v[102:103], v110 offset:20480
	ds_read_b64_tr_b16 v[104:105], v112 offset:22528
	ds_read_b64_tr_b16 v[106:107], v110 offset:24576
	ds_read_b64_tr_b16 v[108:109], v112 offset:26624
	ds_read_b64_tr_b16 v[110:111], v110 offset:28672
	ds_read_b64_tr_b16 v[112:113], v112 offset:30720
	v_mfma_f32_32x32x16_bf16 v[50:65], v[146:149], v[90:93], v[50:65]
	v_mfma_f32_32x32x16_bf16 v[50:65], v[154:157], v[86:89], v[50:65]
	v_mfma_f32_32x32x16_bf16 v[50:65], v[158:161], v[94:97], v[50:65]
	v_mfma_f32_32x32x16_bf16 v[34:49], v[134:137], v[82:85], v[34:49]
	v_mfma_f32_32x32x16_bf16 v[34:49], v[130:133], v[90:93], v[34:49]
	v_mfma_f32_32x32x16_bf16 v[34:49], v[138:141], v[86:89], v[34:49]
	v_mfma_f32_32x32x16_bf16 v[34:49], v[142:145], v[94:97], v[34:49]
	v_add_u32_e32 v142, v210, v208
	v_add_u32_e32 v144, v211, v208
	ds_read_b64_tr_b16 v[130:131], v142 offset:16384
	ds_read_b64_tr_b16 v[132:133], v144 offset:18432
	ds_read_b64_tr_b16 v[134:135], v142 offset:20480
	ds_read_b64_tr_b16 v[136:137], v144 offset:22528
	ds_read_b64_tr_b16 v[138:139], v142 offset:24576
	ds_read_b64_tr_b16 v[140:141], v144 offset:26624
	ds_read_b64_tr_b16 v[142:143], v142 offset:28672
	ds_read_b64_tr_b16 v[144:145], v144 offset:30720
	s_waitcnt lgkmcnt(0)
	v_mfma_f32_32x32x16_bf16 v[18:33], v[98:101], v[82:85], v[18:33]
	v_add_f32_e32 v205, v205, v212
	v_mfma_f32_32x32x16_bf16 v[2:17], v[130:133], v[82:85], v[2:17]
	v_mfma_f32_32x32x16_bf16 v[18:33], v[102:105], v[90:93], v[18:33]
	v_mfma_f32_32x32x16_bf16 v[2:17], v[134:137], v[90:93], v[2:17]
	v_mfma_f32_32x32x16_bf16 v[18:33], v[106:109], v[86:89], v[18:33]
	v_mfma_f32_32x32x16_bf16 v[2:17], v[138:141], v[86:89], v[2:17]
	v_mfma_f32_32x32x16_bf16 v[18:33], v[110:113], v[94:97], v[18:33]
	v_mfma_f32_32x32x16_bf16 v[2:17], v[142:145], v[94:97], v[2:17]

; template <bool DIFF> ...
;     ...
;     for (int kt = DIFF ? nkt - 1 : 0; DIFF ? (kt >= 0) : (kt < nkt); kt += DIFF ? -1 : 1, ++it) {
;         if (DIFF) asm volatile("s_waitcnt vmcnt(0)" ::: "memory");
;         __syncthreads();
.LBB0_114:
	s_add_i32 s0, s20, s22
	s_cmp_lt_u32 s0, 64
	s_cbranch_scc1 .Latt_w0
	s_waitcnt vmcnt(4)
	s_branch .Latt_w1

; #define LAS __attribute__((address_space(3)))
; template <bool DIFF> ...
;     ...
;     for (int kt = DIFF ? nkt - 1 : 0; DIFF ? (kt >= 0) : (kt < nkt); kt += DIFF ? -1 : 1, ++it) {
;         if (DIFF) asm volatile("s_waitcnt vmcnt(0)" ::: "memory");
;         __syncthreads();
;         if (DIFF) { if (kt > 0) ATT_DMA(kt - 1, (it + 1) & 1); }
;         else { ATT_LSTORE(0); if (kt + 1 < nkt) ATT_GLOAD(kt + 1); __syncthreads(); }
;         const bool active = DIFF ? (64 * kt <= wrow) : true;
;         if (active) {
;             LAS const unsigned char* kb = DIFF ? lds + (it & 1) * DSTG : lds; LAS const unsigned char* vb = DIFF ? kb + 16384 : kb + KBY;
;             LAS const unsigned char* qa = lds + QOFF + (qr + l32) * QSTR + hi * 16;
;             f32x16 s0 = biasv, s1 = biasv;
;             LAS const unsigned char* ka = kb + l32 * KSTR + (DIFF ? c * 128 : 0) + hi * 16;
; #pragma unroll 1
;             for (int kq = 0; kq < NKS; kq += 4) {
;                 bf16x8 ka0[4], ka1[4], qq[4];
; #pragma unroll
;                 for (int j = 0; j < 4; ++j) {
;                     if (DIFF) { const int ko = 256 * l32 + 16 * (((c << 3) + 2 * j + hi) ^ (((l32 & 3) << 2) | ((l32 >> 2) & 3)));
;                         ka0[j] = *(LAS const bf16x8*)(kb + ko); ka1[j] = *(LAS const bf16x8*)(kb + 8192 + ko); }
;                     else { ka0[j] = *(LAS const bf16x8*)(ka + (kq + j) * 32); ka1[j] = *(LAS const bf16x8*)(ka + 32 * KSTR + (kq + j) * 32); }
;                     qq[j] = DIFF ? qf[DIFF ? j : 0] : *(LAS const bf16x8*)(qa + (kq + j) * 32); }
;                 __builtin_amdgcn_sched_barrier(0);
; #pragma unroll
;                 for (int j = 0; j < 4; ++j) { s0 = __builtin_amdgcn_mfma_f32_32x32x16_bf16(ka0[j], qq[j], s0, 0, 0, 0); s1 = __builtin_amdgcn_mfma_f32_32x32x16_bf16(ka1[j], qq[j], s1, 0, 0, 0); }
;             }
;             float c0 = 0.f, c1 = 0.f;
;             if (DIFF) {
;                 c0 = sl2 * (float)(64 * kt - wrow); c1 = sl2 * (float)(64 * kt + 32 - wrow);
;                 if (64 * kt + 64 > wrow) {
;                     asm volatile("" ::: "memory");
;                     const int irel = wrow + l32 - 64 * kt - hi * 4;
; #pragma unroll
;                     for (int r = 0; r < 16; ++r) { const int cr = (r >> 2) * 8 + (r & 3); if (cr > irel) s0[r] = -INFINITY; if (cr + 32 > irel) s1[r] = -INFINITY; }
;                 }
.Latt_w1:
	s_waitcnt lgkmcnt(0)
	s_barrier
	s_cmp_lt_u32 s0, 0x80
	s_cbranch_scc1 .LBB0_116
	s_add_i32 s0, s28, 0x10000
	s_and_b32 s0, s0, 0x18000
	s_add_i32 s0, s0, 0
	v_lshl_add_u64 v[82:83], v[168:169], 0, v[0:1]
	s_add_i32 s1, s0, s21
	v_lshl_add_u64 v[84:85], v[82:83], 0, s[42:43]
	s_mov_b32 m0, s1
	v_lshl_add_u64 v[82:83], v[82:83], 0, s[6:7]
	global_load_lds_dwordx4 v[84:85], off
	s_add_i32 m0, s1, 0x4000
	s_add_i32 s0, s0, s14
	global_load_lds_dwordx4 v[82:83], off
	v_lshl_add_u64 v[82:83], v[166:167], 0, v[0:1]
	v_lshl_add_u64 v[84:85], v[82:83], 0, s[42:43]
	s_mov_b32 m0, s0
	v_lshl_add_u64 v[82:83], v[82:83], 0, s[6:7]
	global_load_lds_dwordx4 v[84:85], off
	s_add_i32 m0, s0, 0x4000
	s_nop 0
	global_load_lds_dwordx4 v[82:83], off
.LBB0_116:
	s_add_i32 s0, s25, s22
	s_add_i32 s1, s0, 64
	s_cmp_gt_u32 s1, s15
	s_cbranch_scc1 .Latt_inact
	s_and_b32 s1, s28, 0x18000
	s_add_i32 s23, s1, 0
	v_add_u32_e32 v86, s23, v200
	ds_read_b128 v[82:85], v86
	ds_read_b128 v[130:133], v86 offset:8192
	v_add_u32_e32 v86, s23, v201
	ds_read_b128 v[134:137], v86
	ds_read_b128 v[138:141], v86 offset:8192
	v_add_u32_e32 v86, s23, v202
	ds_read_b128 v[142:145], v86
	ds_read_b128 v[146:149], v86 offset:8192
	v_add_u32_e32 v86, s23, v203
	ds_read_b128 v[150:153], v86
	ds_read_b128 v[154:157], v86 offset:8192
	s_waitcnt lgkmcnt(0)
	v_mfma_f32_32x32x16_bf16 v[98:113], v[82:85], v[114:117], v[66:81]
	s_addk_i32 s0, 0x80
	s_cmp_le_u32 s0, s15
	v_mfma_f32_32x32x16_bf16 v[82:97], v[130:133], v[114:117], v[66:81]
	v_mfma_f32_32x32x16_bf16 v[98:113], v[134:137], v[118:121], v[98:113]
	v_mfma_f32_32x32x16_bf16 v[82:97], v[138:141], v[118:121], v[82:97]
	v_mfma_f32_32x32x16_bf16 v[98:113], v[142:145], v[122:125], v[98:113]
	v_mfma_f32_32x32x16_bf16 v[82:97], v[146:149], v[122:125], v[82:97]
	v_mfma_f32_32x32x16_bf16 v[98:113], v[150:153], v[126:129], v[98:113]
	v_mfma_f32_32x32x16_bf16 v[82:97], v[154:157], v[126:129], v[82:97]
	s_cbranch_scc1 .LBB0_119
	v_cmp_gt_i32_e64 s[94:95], 26, v204
	s_mov_b64 s[2:3], s[96:97]
	v_cmp_gt_i32_e64 s[96:97], 27, v204
	v_cmp_gt_i32_e64 s[92:93], 25, v204
	s_and_b64 s[94:95], s[96:97], s[94:95]
	v_cmp_gt_i32_e64 s[90:91], 24, v204
	s_and_b64 s[92:93], s[94:95], s[92:93]
	v_cmp_gt_i32_e64 s[88:89], 19, v204
	s_and_b64 s[90:91], s[92:93], s[90:91]
	v_cmp_gt_i32_e64 s[86:87], 18, v204
	s_and_b64 s[88:89], s[90:91], s[88:89]
	v_cmp_gt_i32_e64 s[84:85], 17, v204
	s_and_b64 s[86:87], s[88:89], s[86:87]
	v_cmp_gt_i32_e64 s[82:83], 16, v204
	s_and_b64 s[84:85], s[86:87], s[84:85]
	v_cmp_gt_i32_e64 s[80:81], 11, v204
	s_and_b64 s[82:83], s[84:85], s[82:83]
	v_cmp_gt_i32_e64 s[78:79], 10, v204
	s_and_b64 s[80:81], s[82:83], s[80:81]
	v_cmp_gt_i32_e64 s[76:77], 9, v204
	s_and_b64 s[78:79], s[80:81], s[78:79]
	v_cmp_gt_i32_e64 s[74:75], 8, v204
	s_and_b64 s[76:77], s[78:79], s[76:77]
	v_cmp_gt_i32_e64 s[72:73], 3, v204
	s_and_b64 s[74:75], s[76:77], s[74:75]
	v_cmp_gt_i32_e64 s[70:71], 2, v204
	s_and_b64 s[72:73], s[74:75], s[72:73]
	v_cmp_gt_i32_e64 s[68:69], 1, v204
	s_and_b64 s[70:71], s[72:73], s[70:71]
	v_cmp_gt_i32_e64 s[66:67], 0, v204
	s_and_b64 s[68:69], s[70:71], s[68:69]
	s_and_b64 s[66:67], s[68:69], s[66:67]
	v_cmp_gt_i32_e64 s[62:63], 58, v204
	v_cndmask_b32_e64 v98, v98, v193, s[66:67]
	v_cmp_gt_i32_e64 s[66:67], 59, v204
	v_cmp_gt_i32_e64 s[60:61], 57, v204
	s_and_b64 s[62:63], s[66:67], s[62:63]
	v_cmp_gt_i32_e64 s[58:59], 56, v204
	s_and_b64 s[60:61], s[62:63], s[60:61]
	v_cmp_gt_i32_e64 s[56:57], 51, v204
	s_and_b64 s[58:59], s[60:61], s[58:59]
	v_cmp_gt_i32_e64 s[54:55], 50, v204
	s_and_b64 s[56:57], s[58:59], s[56:57]
	v_cmp_gt_i32_e64 s[52:53], 49, v204
	s_and_b64 s[54:55], s[56:57], s[54:55]
	v_cmp_gt_i32_e64 s[50:51], 48, v204
	s_and_b64 s[52:53], s[54:55], s[52:53]
	v_cmp_gt_i32_e64 s[48:49], 43, v204
	s_and_b64 s[50:51], s[52:53], s[50:51]
	v_cmp_gt_i32_e64 s[46:47], 42, v204
	s_and_b64 s[48:49], s[50:51], s[48:49]
	v_cmp_gt_i32_e64 s[42:43], 41, v204
	s_and_b64 s[46:47], s[48:49], s[46:47]
	v_cmp_gt_i32_e64 s[40:41], 40, v204
	s_and_b64 s[42:43], s[46:47], s[42:43]
	v_cmp_gt_i32_e64 s[38:39], 35, v204
	s_and_b64 s[40:41], s[42:43], s[40:41]
	v_cmp_gt_i32_e64 s[36:37], 34, v204
	s_and_b64 s[38:39], s[40:41], s[38:39]
	v_cmp_gt_i32_e64 s[0:1], 33, v204
	s_and_b64 s[36:37], s[38:39], s[36:37]
	v_cmp_gt_i32_e32 vcc, 32, v204
	s_and_b64 s[0:1], s[36:37], s[0:1]
	s_and_b64 vcc, s[0:1], vcc
	v_cndmask_b32_e64 v113, v113, v193, s[96:97]
	s_mov_b64 s[96:97], s[2:3]
	v_cndmask_b32_e64 v112, v112, v193, s[94:95]
	v_cndmask_b32_e64 v111, v111, v193, s[92:93]
	v_cndmask_b32_e64 v110, v110, v193, s[90:91]
	v_cndmask_b32_e64 v109, v109, v193, s[88:89]
	v_cndmask_b32_e64 v108, v108, v193, s[86:87]
	v_cndmask_b32_e64 v107, v107, v193, s[84:85]
	v_cndmask_b32_e64 v106, v106, v193, s[82:83]
	v_cndmask_b32_e64 v105, v105, v193, s[80:81]
	v_cndmask_b32_e64 v104, v104, v193, s[78:79]
	v_cndmask_b32_e64 v103, v103, v193, s[76:77]
	v_cndmask_b32_e64 v102, v102, v193, s[74:75]
	v_cndmask_b32_e64 v101, v101, v193, s[72:73]
	v_cndmask_b32_e64 v100, v100, v193, s[70:71]
	v_cndmask_b32_e64 v99, v99, v193, s[68:69]
	v_cndmask_b32_e64 v97, v97, v193, s[66:67]
	v_cndmask_b32_e64 v96, v96, v193, s[62:63]
	v_cndmask_b32_e64 v95, v95, v193, s[60:61]
	v_cndmask_b32_e64 v94, v94, v193, s[58:59]
	v_cndmask_b32_e64 v93, v93, v193, s[56:57]
	v_cndmask_b32_e64 v92, v92, v193, s[54:55]
	v_cndmask_b32_e64 v91, v91, v193, s[52:53]
	v_cndmask_b32_e64 v90, v90, v193, s[50:51]
	v_cndmask_b32_e64 v89, v89, v193, s[48:49]
	v_cndmask_b32_e64 v88, v88, v193, s[46:47]
	s_mov_b64 s[46:47], 0x1000
	v_cndmask_b32_e64 v87, v87, v193, s[42:43]
	s_mov_b64 s[42:43], 0xa110400
	v_cndmask_b32_e64 v86, v86, v193, s[40:41]
	v_cndmask_b32_e64 v85, v85, v193, s[38:39]
	v_cndmask_b32_e64 v84, v84, v193, s[36:37]
	v_cndmask_b32_e64 v83, v83, v193, s[0:1]
	v_cndmask_b32_e32 v82, v82, v193, vcc

; #define ATT_GLOAD(kt) do { _Pragma("unroll") for (int i = 0; i < NCH; ++i) { const size_t go = goff + (size_t)((kt) * 64 + i * (512 / CPR)) * kvpitch; \
;         kreg[i] = *(const u32x4*)(Kp + go); vreg[i] = *(const u32x4*)(Vp + go); } } while (0)
; #define ATT_LSTORE(buf) do { LAS unsigned char* bb = lds + (buf) * STAGE; _Pragma("unroll") for (int i = 0; i < NCH; ++i) { \
;         *(LAS u32x4*)(bb + loffk + i * (512 / CPR) * KSTR) = kreg[i]; *(LAS u32x4*)(bb + loffv + i * (512 / CPR) * VSTR) = vreg[i]; } } while (0)
; template <bool DIFF> ...
;     ...
;         if (DIFF) asm volatile("s_waitcnt vmcnt(0)" ::: "memory");
;         __syncthreads();
;         if (DIFF) { if (kt > 0) ATT_DMA(kt - 1, (it + 1) & 1); }
;         else { ATT_LSTORE(0); if (kt + 1 < nkt) ATT_GLOAD(kt + 1); __syncthreads(); }
;         const bool active = DIFF ? (64 * kt <= wrow) : true;
;         if (active) {
;     ...
;     if (DIFF) {
;         __syncthreads();
.Latt_i0:
	s_waitcnt vmcnt(0)
.Latt_i1:
	s_barrier
	s_branch .LBB0_113
.LBB0_121:
	s_cmp_eq_u32 s64, 0
	s_cbranch_scc0 .Latt_noalign
	s_barrier
